# v40 plus static s_setprio 1 for waves 4-7 during attention units
# baseline (speedup 1.0000x reference)
; __device__ __forceinline__ int otid() { int t = threadIdx.x; asm volatile("" : "+v"(t)); return t; }
; #define WAIT_BAR(N) asm volatile("s_waitcnt vmcnt(" #N ") lgkmcnt(0)\n\ts_barrier":::"memory")
;   #define DMA_K(t,slot) glds16(ksrc+(long)(t)*KVBLK*KVP,(unsigned)__builtin_amdgcn_readfirstlane(kdst+(slot)))
;   #define DMA_V(t,slot) glds16(vsrc+(long)(t)*KVBLK*KVP,(unsigned)__builtin_amdgcn_readfirstlane(vdst+(slot)))
;   #define CMASK(P0,P1,t) do{}while(0)
;   #define CMASK(P0,P1,t) do{}while(0)
;   #define CMASK(P0,P1,t) do{}while(0)
; template<int THRL> __device__ __forceinline__ void attn_unit(const bf16*Qu,const bf16*__restrict__ Kh,const bf16*__restrict__ Vh,bf16*Ou,const int NT,const float shift,char*shm){
;   const int tid=otid(),lane=tid&63,r32=lane&31,hi=lane>>5; const int wid=__builtin_amdgcn_readfirstlane(tid>>6);
;   const bf16*Qw=Qu+(long)wid*QBLK*QP;
;   const unsigned lds0=(unsigned)(uintptr_t)shm;
;   float*wsf=(float*)(shm+LDS_WS)+wid*64;
;   const bf16*ksrc=Kh+(long)lane*KVP+wid*8;
;   const bf16*vsrc=Vh+(long)(16*(wid&3)+(lane>>2))*KVP+(wid>>2)*32+(lane&3)*8;
;   const unsigned kdst=lds0+LDS_K+wid*1024, vdst=lds0+LDS_V+wid*1024;
;     ...
;   const int vb0=(int)(lds0+LDS_V)+((lane>>4)&1)*32+(lane&3)*8+(4*hi+((lane&15)>>2))*64;
;   const char*Kbase=shm+LDS_K; bf16x8 kf[8];
;   const lds_cptr shm3=(lds_cptr)shm; const lds_cptr kp0=shm3+LDS_K+hi*1024+r32*16; const lds_cptr vp0=shm3+LDS_V+((lane>>4)&1)*32+(lane&3)*8+(4*hi+((lane&15)>>2))*64;
;   DMA_K(0,0);DMA_V(0,0);DMA_K(1,SLOTB);
;   bf16x8 qr[4];
;   #pragma unroll
;   for(int d0=0;d0<4;++d0)qr[d0]=*reinterpret_cast<const bf16x8*>(&Qw[(long)r32*QP+d0*16+hi*8]);
;   float mhat=0.f,l_reg=0.f;f32x16 o[2];o[0]=f32x16{};o[1]=f32x16{};f32x16 negm=f32x16{};asm volatile("":"+v"(negm));
;     ...
;   bool resc=false;
;     ...
;   f32x16 pA0,pA1,pB0,pB1;
;   int sl_prev=0,sl_cur=0,sl_next=SLOTB;
;     ...
;   DMA_K(2,2*SLOTB);
;   WAIT_BAR(3);
;   qkt(pA0,pA1,Kbase,qr,negm,r32,hi);asm volatile("s_nop 15\n\ts_nop 7":"+v"(pA0),"+v"(pA1));CMASK(pA0,pA1,0);
;   START(pA0,pA1);
;   _Pragma("unroll") for(int r=0;r<16;++r)pA1[r]=__builtin_amdgcn_exp2f(pA1[r]);
;   WAIT_BAR(0);
.LBB0_616:
	s_lshl_b32 s4, s84, 1
	s_ashr_i32 s5, s82, 2
	s_add_i32 s6, s4, s5
	v_readlane_b32 s4, v246, 62
	v_readlane_b32 s5, v246, 63
	s_lshl_b64 s[4:5], s[4:5], 11
	s_add_u32 s7, s57, s4
	s_addc_u32 s24, s58, s5
	s_lshl_b32 s4, s82, 6
	s_ashr_i32 s5, s4, 31
	s_lshl_b64 s[48:49], s[4:5], 1
	s_add_u32 s26, s7, s48
	s_addc_u32 s27, s24, s49
	s_mul_hi_i32 s7, s6, 0x208000
	s_mul_i32 s6, s6, 0x208000
	s_add_u32 s4, s59, s6
	s_addc_u32 s5, s60, s7
	v_mov_b32_e32 v42, v216
	s_add_u32 s6, s61, s6
	s_addc_u32 s7, s62, s7
	v_readfirstlane_b32 s69, v42
	s_ashr_i32 s44, s69, 6
	s_cmp_lt_u32 s44, 4
	s_cbranch_scc1 .Lprio_skip
	s_setprio 1
.Lprio_skip:
	s_ashr_i32 s45, s44, 31
	v_and_b32_e32 v238, 63, v42
	s_lshl_b64 s[24:25], s[44:45], 16
	s_add_u32 s24, s26, s24
	v_lshlrev_b32_e32 v0, 4, v42
	s_addc_u32 s25, s27, s25
	v_lshl_add_u64 v[2:3], s[4:5], 0, v[0:1]
	s_mov_b32 s4, 0
	s_ashr_i32 s5, s4, 31
	v_lshl_add_u64 v[212:213], s[4:5], 1, v[2:3]
	s_lshl_b32 s4, s44, 4
	v_bfe_u32 v0, v42, 2, 4
	v_and_or_b32 v0, s4, 48, v0
	s_ashr_i32 s4, s69, 3
	s_andn2_b32 s4, s4, 31
	v_lshlrev_b32_e32 v0, 7, v0
	s_ashr_i32 s5, s4, 31
	s_lshl_b32 s70, s44, 10
	v_lshl_add_u64 v[2:3], s[6:7], 0, v[0:1]
	v_lshlrev_b32_e32 v239, 3, v42
	s_cmp_lg_u32 0, -1
	v_lshl_add_u64 v[2:3], s[4:5], 1, v[2:3]
	v_and_b32_e32 v242, 24, v239
	s_cselect_b32 s4, 0, 0
	v_and_b32_e32 v240, 31, v42
	v_lshlrev_b32_e32 v0, 4, v42
	s_add_i32 s70, s70, s4
	s_mov_b32 s4, m0
	s_mov_b32 m0, s70
	s_nop 0
	global_load_lds_dwordx4 v[212:213], off
	s_mov_b32 m0, s4
	v_bfe_u32 v241, v42, 5, 1
	v_lshl_add_u64 v[214:215], s[6:7], 0, v[0:1]
	s_add_i32 s71, s70, 0x6000
	s_mov_b32 s4, m0
	s_mov_b32 m0, s71
	s_nop 0
	global_load_lds_dwordx4 v[214:215], off
	s_mov_b32 m0, s4
	s_mov_b64 s[26:27], 0x2000
	v_lshlrev_b32_e32 v0, 11, v240
	v_lshl_add_u64 v[2:3], v[212:213], 0, s[26:27]
	s_add_i32 s4, s70, 0x2000
	s_mov_b32 s5, m0
	s_mov_b32 m0, s4
	s_nop 0
	global_load_lds_dwordx4 v[2:3], off
	s_mov_b32 m0, s5
	v_lshl_or_b32 v0, v241, 4, v0
	global_load_dwordx4 v[150:153], v0, s[24:25]
	global_load_dwordx4 v[138:141], v0, s[24:25] offset:32
	global_load_dwordx4 v[134:137], v0, s[24:25] offset:64
	global_load_dwordx4 v[130:133], v0, s[24:25] offset:96
	v_mov_b32_e32 v2, v1
	v_mov_b32_e32 v3, v1
	v_mov_b32_e32 v4, v1
	v_mov_b32_e32 v5, v1
	v_mov_b32_e32 v6, v1
	v_mov_b32_e32 v7, v1
	v_mov_b32_e32 v8, v1
	v_mov_b32_e32 v9, v1
	v_mov_b32_e32 v10, v1
	v_mov_b32_e32 v11, v1
	v_mov_b32_e32 v12, v1
	v_mov_b32_e32 v13, v1
	v_mov_b32_e32 v14, v1
	v_mov_b32_e32 v15, v1
	v_lshlrev_b32_e32 v0, 10, v241
	v_lshlrev_b32_e32 v16, 4, v240
	v_add3_u32 v244, 0, v0, v16
	v_mov_b32_e32 v0, v1
	v_mov_b64_e32 v[16:17], v[14:15]
	v_mov_b64_e32 v[14:15], v[12:13]
	v_mov_b64_e32 v[12:13], v[10:11]
	v_mov_b64_e32 v[10:11], v[8:9]
	v_mov_b64_e32 v[8:9], v[6:7]
	v_mov_b64_e32 v[6:7], v[4:5]
	v_mov_b64_e32 v[4:5], v[2:3]
	v_mov_b64_e32 v[2:3], v[0:1]
	v_lshl_add_u64 v[18:19], v[212:213], 0, s[72:73]
	s_add_i32 s4, s70, 0x4000
	s_mov_b32 s5, m0
	s_mov_b32 m0, s4
	s_nop 0
	global_load_lds_dwordx4 v[18:19], off
	s_mov_b32 m0, s5
	s_waitcnt vmcnt(3) lgkmcnt(0)
	s_barrier
	ds_read_b128 v[34:37], v244
	ds_read_b128 v[38:41], v244 offset:512
	v_lshlrev_b32_e32 v0, 1, v42
	v_and_b32_e32 v243, 32, v0
	s_mov_b64 s[34:35], 0x6000
	v_add_u32_e32 v50, 0, v243
	s_mov_b32 s5, 1
	s_mov_b32 s4, 0
	s_movk_i32 s31, 0x2000
	s_mov_b32 s24, 0
	s_movk_i32 s76, 0x4000
	s_waitcnt vmcnt(3) lgkmcnt(1)
	v_mfma_f32_32x32x16_bf16 v[18:33], v[34:37], v[150:153], v[2:17]
	s_waitcnt lgkmcnt(0)
	v_mfma_f32_32x32x16_bf16 v[2:17], v[38:41], v[150:153], v[2:17]
	ds_read_b128 v[34:37], v244 offset:2048
	ds_read_b128 v[38:41], v244 offset:2560
	s_waitcnt vmcnt(2) lgkmcnt(1)
	v_mfma_f32_32x32x16_bf16 v[18:33], v[34:37], v[138:141], v[18:33]
	s_waitcnt lgkmcnt(0)
	v_mfma_f32_32x32x16_bf16 v[2:17], v[38:41], v[138:141], v[2:17]
	ds_read_b128 v[34:37], v244 offset:4096
	ds_read_b128 v[38:41], v244 offset:4608
	s_waitcnt vmcnt(1) lgkmcnt(1)
	v_mfma_f32_32x32x16_bf16 v[18:33], v[34:37], v[134:137], v[18:33]
	ds_read_b128 v[34:37], v244 offset:6144
	s_waitcnt lgkmcnt(1)
	v_mfma_f32_32x32x16_bf16 v[2:17], v[38:41], v[134:137], v[2:17]
	ds_read_b128 v[38:41], v244 offset:6656
	s_waitcnt vmcnt(0) lgkmcnt(1)
	v_mfma_f32_32x32x16_bf16 v[18:33], v[34:37], v[130:133], v[18:33]
	v_add_f32_e32 v34, v1, v237
	v_lshlrev_b32_e32 v35, 4, v42
	v_xor_b32_e32 v34, 0x80000000, v34
	v_and_b32_e32 v0, 0xc0, v35
	v_mov_b32_e32 v35, v34
	v_mov_b32_e32 v36, v34
	v_mov_b32_e32 v37, v34
	s_waitcnt lgkmcnt(0)
	v_mfma_f32_32x32x16_bf16 v[2:17], v[38:41], v[130:133], v[2:17]
	s_nop 15
	s_nop 7
	v_mov_b32_e32 v38, v34
	v_mov_b32_e32 v39, v34
	v_mov_b32_e32 v40, v34
	v_mov_b32_e32 v41, v34
	v_mov_b32_e32 v42, v34
	v_mov_b32_e32 v43, v34
	v_mov_b32_e32 v44, v34
	v_mov_b32_e32 v45, v34
	v_mov_b32_e32 v46, v34
	v_mov_b32_e32 v47, v34
	v_mov_b32_e32 v48, v34
	v_mov_b32_e32 v49, v34
	v_sub_f32_e32 v2, v2, v237
	v_sub_f32_e32 v3, v3, v237
	s_waitcnt vmcnt(0) lgkmcnt(0)
	s_barrier
; #define WAIT_BAR(N) asm volatile("s_waitcnt vmcnt(" #N ") lgkmcnt(0)\n\ts_barrier":::"memory")
;   #define DMA_K(t,slot) glds16(ksrc+(long)(t)*KVBLK*KVP,(unsigned)__builtin_amdgcn_readfirstlane(kdst+(slot)))
;   #define DMA_V(t,slot) glds16(vsrc+(long)(t)*KVBLK*KVP,(unsigned)__builtin_amdgcn_readfirstlane(vdst+(slot)))
;   #define ROT() do{sl_prev=sl_cur;sl_cur=sl_next;sl_next=(sl_next==(NSLOT-1)*SLOTB)?0:sl_next+SLOTB;}while(0)
; template<int THRL> __device__ __forceinline__ void attn_unit(const bf16*Qu,const bf16*__restrict__ Kh,const bf16*__restrict__ Vh,bf16*Ou,const int NT,const float shift,char*shm){
;     ...
;   WAIT_BAR(0);
;   DMA_K(3,0);DMA_V(1,SLOTB);
;   ROT();
;   kload8(kf,kp0+sl_cur);
;   WAIT_BAR(2);
;   s16x4 vlo[8],vhi[8]; u32x4 pw0,pw1,pw2,pw3;
	v_sub_f32_e32 v18, v18, v237
	v_sub_f32_e32 v19, v19, v237
	s_nop 0
	v_exp_f32_e32 v66, v2
	v_exp_f32_e32 v67, v3
	v_lshl_add_u64 v[2:3], v[212:213], 0, s[34:35]
	s_mov_b32 s6, m0
	s_mov_b32 m0, s70
	s_nop 0
	global_load_lds_dwordx4 v[2:3], off
	s_mov_b32 m0, s6
	v_lshl_add_u64 v[2:3], v[214:215], 0, s[26:27]
	s_add_i32 s6, s70, 0x8000
	s_mov_b32 s7, m0
	s_mov_b32 m0, s6
	s_nop 0
	global_load_lds_dwordx4 v[2:3], off
	s_mov_b32 m0, s7
	ds_read_b128 v[190:193], v244 offset:8192
	ds_read_b128 v[186:189], v244 offset:8704
	ds_read_b128 v[182:185], v244 offset:10240
	ds_read_b128 v[178:181], v244 offset:10752
	ds_read_b128 v[174:177], v244 offset:12288
	ds_read_b128 v[170:173], v244 offset:12800
	ds_read_b128 v[166:169], v244 offset:14336
	ds_read_b128 v[162:165], v244 offset:14848
	v_sub_f32_e32 v20, v20, v237
	v_sub_f32_e32 v4, v4, v237
	v_sub_f32_e32 v21, v21, v237
	v_sub_f32_e32 v5, v5, v237
	v_sub_f32_e32 v22, v22, v237
	v_sub_f32_e32 v6, v6, v237
	v_sub_f32_e32 v23, v23, v237
	v_sub_f32_e32 v7, v7, v237
	v_sub_f32_e32 v24, v24, v237
	v_sub_f32_e32 v8, v8, v237
	v_sub_f32_e32 v25, v25, v237
	v_sub_f32_e32 v9, v9, v237
	v_sub_f32_e32 v26, v26, v237
	v_sub_f32_e32 v10, v10, v237
	v_sub_f32_e32 v27, v27, v237
	v_sub_f32_e32 v11, v11, v237
	v_sub_f32_e32 v28, v28, v237
	v_sub_f32_e32 v12, v12, v237
	v_sub_f32_e32 v29, v29, v237
	v_sub_f32_e32 v13, v13, v237
	v_sub_f32_e32 v30, v30, v237
	v_sub_f32_e32 v14, v14, v237
	v_sub_f32_e32 v31, v31, v237
	v_sub_f32_e32 v15, v15, v237
	v_sub_f32_e32 v32, v32, v237
	v_sub_f32_e32 v16, v16, v237
	v_sub_f32_e32 v33, v33, v237
	v_sub_f32_e32 v17, v17, v237
	v_exp_f32_e32 v82, v18
	v_exp_f32_e32 v83, v19
	v_exp_f32_e32 v84, v20
	v_exp_f32_e32 v85, v21
	v_exp_f32_e32 v86, v22
	v_exp_f32_e32 v87, v23
	v_exp_f32_e32 v88, v24
	v_exp_f32_e32 v89, v25
	v_exp_f32_e32 v90, v26
	v_exp_f32_e32 v91, v27
	v_exp_f32_e32 v92, v28
	v_exp_f32_e32 v93, v29
	v_exp_f32_e32 v94, v30
	v_exp_f32_e32 v95, v31
	v_exp_f32_e32 v96, v32
	v_exp_f32_e32 v97, v33
	v_exp_f32_e32 v68, v4
	v_exp_f32_e32 v69, v5
	v_exp_f32_e32 v70, v6
	v_exp_f32_e32 v71, v7
	v_exp_f32_e32 v72, v8
	v_exp_f32_e32 v73, v9
	v_exp_f32_e32 v74, v10
	v_exp_f32_e32 v75, v11
	v_exp_f32_e32 v76, v12
	v_exp_f32_e32 v77, v13
	v_exp_f32_e32 v78, v14
	v_exp_f32_e32 v79, v15
	v_exp_f32_e32 v80, v16
	v_exp_f32_e32 v81, v17
	s_waitcnt vmcnt(2) lgkmcnt(0)
	s_barrier
	v_lshl_or_b32 v0, v241, 8, v0
	v_add3_u32 v245, v50, v242, v0
	s_cmp_lt_i32 s91, 7
	s_cbranch_scc1 .LBB0_620
	s_mov_b64 s[4:5], 0xa000
	v_add_u32_e32 v51, s24, v245
	v_mov_b32_e32 v50, 0
	v_mov_b32_e32 v194, 0
	v_mov_b32_e32 v195, 0
	v_mov_b32_e32 v196, 0
	v_lshlrev_b32_e32 v197, 4, v238
	v_readfirstlane_b32 s98, v212
	v_readfirstlane_b32 s99, v213
	v_readfirstlane_b32 s100, v214
	v_readfirstlane_b32 s101, v215
	s_add_u32 s98, s98, 0x8000
	s_addc_u32 s99, s99, 0
	s_add_u32 s100, s100, 0x4000
	s_addc_u32 s101, s101, 0
	s_mov_b32 s26, 6
	v_mov_b32_e32 v2, 0
	v_mov_b32_e32 v3, v50
	v_mov_b32_e32 v4, v50
	v_mov_b32_e32 v5, v50
	v_mov_b32_e32 v6, v50
	v_mov_b32_e32 v7, v50
	v_mov_b32_e32 v8, v50
	v_mov_b32_e32 v9, v50
	v_mov_b32_e32 v10, v50
	v_mov_b32_e32 v11, v50
	v_mov_b32_e32 v12, v50
	v_mov_b32_e32 v13, v50
	v_mov_b32_e32 v14, v50
	v_mov_b32_e32 v15, v50
	v_mov_b32_e32 v16, v50
	v_mov_b32_e32 v17, v50
	v_mov_b32_e32 v18, 0
	v_mov_b32_e32 v19, v50
	v_mov_b32_e32 v20, v50
	v_mov_b32_e32 v21, v50
	v_mov_b32_e32 v22, v50
	v_mov_b32_e32 v23, v50
	v_mov_b32_e32 v24, v50
	v_mov_b32_e32 v25, v50
	v_mov_b32_e32 v26, v50
	v_mov_b32_e32 v27, v50
	v_mov_b32_e32 v28, v50
	v_mov_b32_e32 v29, v50
	v_mov_b32_e32 v30, v50
	v_mov_b32_e32 v31, v50
	v_mov_b32_e32 v32, v50
	v_mov_b32_e32 v33, v50

; #define SBAR() __builtin_amdgcn_sched_barrier(0)
; #define WAIT_BAR(N) asm volatile("s_waitcnt vmcnt(" #N ") lgkmcnt(0)\n\ts_barrier":::"memory")
;   #define RESC() do{ if(resc){ asm volatile("s_waitcnt lgkmcnt(0)":::"memory"); \
;       _Pragma("unroll") for(int d_=0;d_<2;++d_) _Pragma("unroll") for(int r=0;r<16;++r)o[d_][r]*=wsf[crow(r,hi)]; } }while(0)
;   #define ROT() do{sl_prev=sl_cur;sl_cur=sl_next;sl_next=(sl_next==(NSLOT-1)*SLOTB)?0:sl_next+SLOTB;}while(0)
;   #define PKW(P,B) cvtpk_s(P[B],P[B+1])
;   #define ENDW(tt) do{ if((tt)+3<NT){WAIT_BAR(2);} else if((tt)+2<NT){WAIT_BAR(1);} else {WAIT_BAR(0);} }while(0)
; template<int THRL> __device__ __forceinline__ void attn_unit(const bf16*Qu,const bf16*__restrict__ Kh,const bf16*__restrict__ Vh,bf16*Ou,const int NT,const float shift,char*shm){
;     ...
;   int t=1;
;     ...
;   for(;t+5<NT;t+=2){
;     STEP(pB0,pB1,pA0,pA1,t,true,true,true);     WAIT_BAR(2); RESC(); ROT();
;     STEP(pA0,pA1,pB0,pB1,t+1,true,true,true);   WAIT_BAR(2); RESC(); ROT();
;   }
;     ...
;   for(;t+1<NT;t+=2){
;     STEP(pB0,pB1,pA0,pA1,t,(t+3<NT),(t+1<NT),(t+1<NT));       ENDW(t);   RESC(); ROT();
;     STEP(pA0,pA1,pB0,pB1,t+1,(t+4<NT),(t+2<NT),(t+2<NT));     ENDW(t+1); RESC(); ROT();
;   }
;   STEP(pB0,pB1,pA0,pA1,NT-1,false,false,false); RESC();
;   { float sacc=pB0[0]+pB0[1]; _Pragma("unroll") for(int r=2;r<16;++r)sacc+=pB0[r]; _Pragma("unroll") for(int r=0;r<16;++r)sacc+=pB1[r]; l_reg+=sacc;
;     pw0=(u32x4){PKW(pB0,0),PKW(pB0,2),PKW(pB0,4),PKW(pB0,6)};pw1=(u32x4){PKW(pB0,8),PKW(pB0,10),PKW(pB0,12),PKW(pB0,14)};pw2=(u32x4){PKW(pB1,0),PKW(pB1,2),PKW(pB1,4),PKW(pB1,6)};pw3=(u32x4){PKW(pB1,8),PKW(pB1,10),PKW(pB1,12),PKW(pB1,14)};
;     SBAR(); pv(o,vb0+sl_cur,PAF(0),PAF(1),PAF(2),PAF(3)); }
.LBB0_656:
	s_and_b32 s4, s69, 0x3fffffc0
	s_cmp_lg_u32 0, -1
	s_cselect_b32 s5, 0, 0
	s_lshl_b32 s4, s4, 2
	s_addk_i32 s5, 0x6000
	s_add_i32 s4, s4, 0
	v_add3_u32 v51, v243, s5, v242
	v_add_u32_e32 v114, s76, v245
	ds_read_b64_tr_b16 v[52:53], v114 offset:24576
	ds_read_b64_tr_b16 v[54:55], v114 offset:25088
	v_add_f32_e32 v56, v82, v83
	v_add_f32_e32 v56, v84, v56
	v_add_f32_e32 v56, v85, v56
	v_add_f32_e32 v56, v86, v56
	v_add_f32_e32 v60, v87, v56
	v_cvt_pk_bf16_f32 v158, v82, v83
	v_cvt_pk_bf16_f32 v159, v84, v85
	s_waitcnt lgkmcnt(9)
	v_mfma_f32_32x32x16_bf16 v[98:113], v[190:193], v[150:153], v[34:49]
	ds_read_b64_tr_b16 v[56:57], v114 offset:28672
	ds_read_b64_tr_b16 v[58:59], v114 offset:29184
	v_add_f32_e32 v60, v88, v60
	v_add_f32_e32 v60, v89, v60
	v_add_f32_e32 v60, v90, v60
	v_add_f32_e32 v64, v91, v60
	v_cvt_pk_bf16_f32 v160, v86, v87
	v_cvt_pk_bf16_f32 v161, v88, v89
	s_waitcnt lgkmcnt(10)
	v_mfma_f32_32x32x16_bf16 v[34:49], v[186:189], v[150:153], v[34:49]
	ds_read_b64_tr_b16 v[60:61], v114 offset:25600
	ds_read_b64_tr_b16 v[62:63], v114 offset:26112
	v_add_f32_e32 v64, v92, v64
	v_add_f32_e32 v64, v93, v64
	v_add_f32_e32 v64, v94, v64
	v_add_f32_e32 v64, v95, v64
	v_cvt_pk_bf16_f32 v154, v90, v91
	v_cvt_pk_bf16_f32 v155, v92, v93
	s_waitcnt lgkmcnt(11)
	v_mfma_f32_32x32x16_bf16 v[98:113], v[182:185], v[138:141], v[98:113]
	ds_read_b64_tr_b16 v[82:83], v114 offset:29696
	ds_read_b64_tr_b16 v[84:85], v114 offset:30208
	v_add_f32_e32 v64, v96, v64
	v_add_f32_e32 v64, v97, v64
	v_add_f32_e32 v64, v66, v64
	v_add_f32_e32 v64, v67, v64
	v_cvt_pk_bf16_f32 v156, v94, v95
	v_cvt_pk_bf16_f32 v157, v96, v97
	s_waitcnt lgkmcnt(12)
	v_mfma_f32_32x32x16_bf16 v[34:49], v[178:181], v[138:141], v[34:49]
	ds_read_b64_tr_b16 v[86:87], v114 offset:26624
	ds_read_b64_tr_b16 v[88:89], v114 offset:27136
	v_add_f32_e32 v64, v68, v64
	v_add_f32_e32 v64, v69, v64
	v_add_f32_e32 v64, v70, v64
	v_add_f32_e32 v90, v71, v64
	v_cvt_pk_bf16_f32 v146, v66, v67
	v_cvt_pk_bf16_f32 v147, v68, v69
	s_waitcnt lgkmcnt(13)
	v_mfma_f32_32x32x16_bf16 v[98:113], v[174:177], v[134:137], v[98:113]
	ds_read_b64_tr_b16 v[64:65], v114 offset:30720
	ds_read_b64_tr_b16 v[66:67], v114 offset:31232
	v_add_f32_e32 v68, v72, v90
	v_add_f32_e32 v68, v73, v68
	v_add_f32_e32 v68, v74, v68
	v_add_f32_e32 v90, v75, v68
	v_cvt_pk_bf16_f32 v148, v70, v71
	v_cvt_pk_bf16_f32 v149, v72, v73
	s_waitcnt lgkmcnt(14)
	v_mfma_f32_32x32x16_bf16 v[34:49], v[170:173], v[134:137], v[34:49]
	ds_read_b64_tr_b16 v[68:69], v114 offset:27648
	ds_read_b64_tr_b16 v[70:71], v114 offset:28160
	v_add_f32_e32 v72, v76, v90
	v_add_f32_e32 v72, v77, v72
	v_add_f32_e32 v72, v78, v72
	v_add_f32_e32 v90, v79, v72
	v_cvt_pk_bf16_f32 v142, v74, v75
	v_cvt_pk_bf16_f32 v143, v76, v77
	s_waitcnt lgkmcnt(14)
	v_mfma_f32_32x32x16_bf16 v[98:113], v[166:169], v[130:133], v[98:113]
	ds_read_b64_tr_b16 v[72:73], v114 offset:31744
	ds_read_b64_tr_b16 v[74:75], v114 offset:32256
	v_add_f32_e32 v76, v80, v90
	v_add_f32_e32 v76, v81, v76
	v_add_f32_e32 v76, 0, v76
	v_cvt_pk_bf16_f32 v144, v78, v79
	v_cvt_pk_bf16_f32 v145, v80, v81
	v_mfma_f32_32x32x16_bf16 v[34:49], v[162:165], v[130:133], v[34:49]
	s_waitcnt lgkmcnt(14)
	v_mfma_f32_32x32x16_bf16 v[2:17], v[158:161], v[52:55], v[2:17]
	s_nop 1
	v_exp_f32_e32 v98, v98
	v_exp_f32_e32 v99, v99
	v_exp_f32_e32 v100, v100
	v_exp_f32_e32 v101, v101
	s_waitcnt lgkmcnt(12)
	v_mfma_f32_32x32x16_bf16 v[18:33], v[158:161], v[56:59], v[18:33]
	v_exp_f32_e32 v102, v102
	v_exp_f32_e32 v103, v103
	v_exp_f32_e32 v104, v104
	v_exp_f32_e32 v105, v105
	s_waitcnt lgkmcnt(10)
	v_mfma_f32_32x32x16_bf16 v[2:17], v[154:157], v[60:63], v[2:17]
	v_exp_f32_e32 v106, v106
	v_exp_f32_e32 v107, v107
	v_exp_f32_e32 v108, v108
	v_exp_f32_e32 v109, v109
	s_waitcnt lgkmcnt(8)
	v_mfma_f32_32x32x16_bf16 v[18:33], v[154:157], v[82:85], v[18:33]
	v_exp_f32_e32 v110, v110
	v_exp_f32_e32 v111, v111
	v_exp_f32_e32 v112, v112
	v_exp_f32_e32 v113, v113
	s_waitcnt lgkmcnt(6)
	v_mfma_f32_32x32x16_bf16 v[2:17], v[146:149], v[86:89], v[2:17]
	v_exp_f32_e32 v34, v34
	v_exp_f32_e32 v35, v35
	v_exp_f32_e32 v36, v36
	v_exp_f32_e32 v37, v37
	s_waitcnt lgkmcnt(4)
	v_mfma_f32_32x32x16_bf16 v[18:33], v[146:149], v[64:67], v[18:33]
	v_exp_f32_e32 v38, v38
	v_exp_f32_e32 v39, v39
	v_exp_f32_e32 v40, v40
	v_exp_f32_e32 v41, v41
	s_waitcnt lgkmcnt(2)
	v_mfma_f32_32x32x16_bf16 v[2:17], v[142:145], v[68:71], v[2:17]
	v_exp_f32_e32 v42, v42
	v_exp_f32_e32 v43, v43
	v_exp_f32_e32 v44, v44
	v_exp_f32_e32 v45, v45
	s_waitcnt lgkmcnt(0)
	v_mfma_f32_32x32x16_bf16 v[18:33], v[142:145], v[72:75], v[18:33]
	v_exp_f32_e32 v46, v46
	v_exp_f32_e32 v47, v47
	v_exp_f32_e32 v48, v48
	v_exp_f32_e32 v49, v49
	v_add_f32_e32 v52, v98, v99
	v_add_f32_e32 v52, v100, v52
	v_add_f32_e32 v52, v101, v52
	v_add_f32_e32 v52, v102, v52
	v_add_f32_e32 v52, v103, v52
	v_add_f32_e32 v52, v104, v52
	v_add_f32_e32 v52, v105, v52
	v_add_f32_e32 v52, v106, v52
	v_add_f32_e32 v52, v107, v52
	v_add_f32_e32 v52, v108, v52
	v_add_f32_e32 v52, v109, v52
	v_add_f32_e32 v52, v110, v52
	v_add_f32_e32 v52, v111, v52
	v_add_f32_e32 v52, v112, v52
	v_add_f32_e32 v52, v113, v52
	v_add_f32_e32 v52, v34, v52
	v_add_f32_e32 v52, v35, v52
	v_add_f32_e32 v52, v36, v52
	v_add_f32_e32 v52, v37, v52
	v_add_f32_e32 v52, v38, v52
	v_add_f32_e32 v52, v39, v52
	v_add_f32_e32 v52, v40, v52
	v_add_f32_e32 v52, v41, v52
	v_add_f32_e32 v52, v42, v52
	v_add_f32_e32 v52, v43, v52
	v_add_f32_e32 v52, v44, v52
	v_add_f32_e32 v52, v45, v52
	v_add_f32_e32 v52, v46, v52
	v_add_f32_e32 v52, v47, v52
	v_add_f32_e32 v52, v48, v52
	v_add_f32_e32 v52, v49, v52
	v_add_f32_e32 v50, v50, v76
	v_add_f32_e32 v50, v50, v52
	v_cvt_pk_bf16_f32 v52, v98, v99
	v_cvt_pk_bf16_f32 v53, v100, v101
	v_cvt_pk_bf16_f32 v54, v102, v103
	v_cvt_pk_bf16_f32 v55, v104, v105
	v_cvt_pk_bf16_f32 v56, v106, v107
	v_cvt_pk_bf16_f32 v57, v108, v109
	v_cvt_pk_bf16_f32 v58, v110, v111
	v_cvt_pk_bf16_f32 v59, v112, v113
	v_cvt_pk_bf16_f32 v34, v34, v35
	v_cvt_pk_bf16_f32 v35, v36, v37
	v_cvt_pk_bf16_f32 v36, v38, v39
	v_cvt_pk_bf16_f32 v37, v40, v41
	v_cvt_pk_bf16_f32 v38, v42, v43
	v_cvt_pk_bf16_f32 v39, v44, v45
	v_cvt_pk_bf16_f32 v40, v46, v47
	v_cvt_pk_bf16_f32 v41, v48, v49
	v_add3_u32 v0, v51, v0, s31
	ds_read_b64_tr_b16 v[42:43],v0 offset:0
	ds_read_b64_tr_b16 v[44:45],v0 offset:512
	ds_read_b64_tr_b16 v[46:47],v0 offset:1024
	ds_read_b64_tr_b16 v[48:49],v0 offset:1536
	ds_read_b64_tr_b16 v[60:61],v0 offset:2048
	ds_read_b64_tr_b16 v[62:63],v0 offset:2560
	ds_read_b64_tr_b16 v[64:65],v0 offset:3072
	ds_read_b64_tr_b16 v[66:67],v0 offset:3584
	s_waitcnt lgkmcnt(0)
; __device__ __forceinline__ int crow(int r,int hi){return (r&3)+8*(r>>2)+4*hi;}
; #define SBAR() __builtin_amdgcn_sched_barrier(0)
; __device__ __forceinline__ int crow(int r, int hi) { return (r & 3) + 8 * (r >> 2) + 4 * hi; }
; template<int THRL> __device__ __forceinline__ void attn_unit(const bf16*Qu,const bf16*__restrict__ Kh,const bf16*__restrict__ Vh,bf16*Ou,const int NT,const float shift,char*shm){
;     ...
;     SBAR(); pv(o,vb0+sl_cur,PAF(0),PAF(1),PAF(2),PAF(3)); }
;     ...
;   {auto rr=__builtin_amdgcn_permlane32_swap(__float_as_uint(l_reg),__float_as_uint(l_reg),false,false);l_reg=__uint_as_float(rr[0])+__uint_as_float(rr[1]);}
;   if(hi==0)wsf[32+r32]=l_reg;asm volatile("s_waitcnt lgkmcnt(0)":::"memory");
;   float rli[16];
;   #pragma unroll
;   for(int r=0;r<16;++r)rli[r]=__builtin_amdgcn_rcpf(wsf[32+crow(r,hi)]);
;   bf16*Ow=Ou+(long)wid*QBLK*OP;
;   { bf16*stg=(bf16*)(shm+LDS_OST)+wid*2048;
;     #pragma unroll
;     for(int r=0;r<16;++r){const int orow=crow(r,hi);
;       #pragma unroll
;       for(int d0=0;d0<2;++d0)stg[orow*64+d0*32+r32]=__float2bfloat16(o[d0][r]*rli[r]);}
;     asm volatile("s_waitcnt lgkmcnt(0)":::"memory");
;     #pragma unroll
;     for(int i=0;i<4;++i){const int row=i*8+(lane>>3),ch=lane&7; const u32x4 v=*(const u32x4*)(stg+row*64+ch*8); ATTN_STORE16(Ow+(long)row*OP+ch*8,v);} }
;   asm volatile("s_waitcnt lgkmcnt(0)\n\ts_barrier":::"memory");
	s_nop 0
	v_mfma_f32_32x32x16_bf16 v[2:17], v[52:55], v[42:45], v[2:17]
	ds_read_b64_tr_b16 v[42:43],v0 offset:4096
	ds_read_b64_tr_b16 v[44:45],v0 offset:4608
	v_mfma_f32_32x32x16_bf16 v[2:17], v[56:59], v[46:49], v[2:17]
	ds_read_b64_tr_b16 v[46:47],v0 offset:5120
	ds_read_b64_tr_b16 v[48:49],v0 offset:5632
	v_mfma_f32_32x32x16_bf16 v[2:17], v[34:37], v[60:63], v[2:17]
	ds_read_b64_tr_b16 v[60:61],v0 offset:6144
	ds_read_b64_tr_b16 v[62:63],v0 offset:6656
	v_mfma_f32_32x32x16_bf16 v[2:17], v[38:41], v[64:67], v[2:17]
	ds_read_b64_tr_b16 v[64:65],v0 offset:7168
	ds_read_b64_tr_b16 v[66:67],v0 offset:7680
	s_waitcnt lgkmcnt(0)
	v_mfma_f32_32x32x16_bf16 v[18:33], v[52:55], v[42:45], v[18:33]
	v_mov_b32_e32 v0, v50
	s_nop 1
	v_permlane32_swap_b32_e32 v50, v0
	v_cmp_gt_u32_e32 vcc, 32, v238
	v_mfma_f32_32x32x16_bf16 v[18:33], v[56:59], v[46:49], v[18:33]
	v_mfma_f32_32x32x16_bf16 v[18:33], v[34:37], v[60:63], v[18:33]
	v_mfma_f32_32x32x16_bf16 v[18:33], v[38:41], v[64:67], v[18:33]
	s_and_saveexec_b64 s[30:31], vcc
	v_add_f32_e32 v0, v50, v0
	v_lshl_add_u32 v34, v240, 2, s4
	ds_write_b32 v34, v0 offset:49280
	s_or_b64 exec, exec, s[30:31]
	s_waitcnt lgkmcnt(0)
	v_lshl_add_u32 v0, v241, 4, s4
	ds_read_b128 v[34:37], v0 offset:49280
	ds_read_b128 v[38:41], v0 offset:49312
	s_lshl_b64 s[6:7], s[26:27], 1
	s_add_u32 s5, s2, s6
	s_addc_u32 s4, s3, s7
	s_waitcnt lgkmcnt(1)
	v_rcp_f32_e32 v42, v34
	v_rcp_f32_e32 v43, v35
	v_rcp_f32_e32 v44, v36
	v_rcp_f32_e32 v45, v37
	s_waitcnt lgkmcnt(0)
	v_rcp_f32_e32 v46, v38
	ds_read_b128 v[34:37], v0 offset:49344
	v_rcp_f32_e32 v47, v39
	v_rcp_f32_e32 v48, v40
	v_rcp_f32_e32 v49, v41
	ds_read_b128 v[38:41], v0 offset:49376
	s_add_u32 s6, s5, s48
	s_addc_u32 s7, s4, s49
	s_lshl_b32 s4, s44, 12
	s_waitcnt lgkmcnt(1)
	v_rcp_f32_e32 v0, v34
	v_rcp_f32_e32 v34, v35
	v_rcp_f32_e32 v35, v36
	v_rcp_f32_e32 v36, v37
	s_waitcnt lgkmcnt(0)
	v_rcp_f32_e32 v37, v38
	v_rcp_f32_e32 v38, v39
	v_rcp_f32_e32 v39, v40
	v_rcp_f32_e32 v40, v41
	s_add_i32 s26, s4, 0
	v_lshlrev_b32_e32 v41, 9, v241
	v_lshlrev_b32_e32 v50, 1, v240
	v_mul_f32_e32 v2, v2, v42
	v_add3_u32 v41, s26, v41, v50
	v_cvt_pk_bf16_f32 v2, v2, s0
	ds_write_b16 v41, v2 offset:51200
	v_mul_f32_e32 v2, v18, v42
	v_cvt_pk_bf16_f32 v2, v2, s0
	ds_write_b16 v41, v2 offset:51264
	v_mul_f32_e32 v2, v3, v43
	v_cvt_pk_bf16_f32 v2, v2, s0
	ds_write_b16 v41, v2 offset:51328
	v_mul_f32_e32 v2, v19, v43
	v_cvt_pk_bf16_f32 v2, v2, s0
	ds_write_b16 v41, v2 offset:51392
	v_mul_f32_e32 v2, v4, v44
	v_cvt_pk_bf16_f32 v2, v2, s0
	ds_write_b16 v41, v2 offset:51456
	v_mul_f32_e32 v2, v20, v44
	v_cvt_pk_bf16_f32 v2, v2, s0
	ds_write_b16 v41, v2 offset:51520
	v_mul_f32_e32 v2, v5, v45
	v_cvt_pk_bf16_f32 v2, v2, s0
	ds_write_b16 v41, v2 offset:51584
	v_mul_f32_e32 v2, v21, v45
	v_cvt_pk_bf16_f32 v2, v2, s0
	ds_write_b16 v41, v2 offset:51648
	v_mul_f32_e32 v2, v6, v46
	v_cvt_pk_bf16_f32 v2, v2, s0
	ds_write_b16 v41, v2 offset:52224
	v_mul_f32_e32 v2, v22, v46
	v_cvt_pk_bf16_f32 v2, v2, s0
	ds_write_b16 v41, v2 offset:52288
	v_mul_f32_e32 v2, v7, v47
	v_cvt_pk_bf16_f32 v2, v2, s0
	ds_write_b16 v41, v2 offset:52352
	v_mul_f32_e32 v2, v23, v47
	v_cvt_pk_bf16_f32 v2, v2, s0
	ds_write_b16 v41, v2 offset:52416
	v_mul_f32_e32 v2, v8, v48
	v_cvt_pk_bf16_f32 v2, v2, s0
	ds_write_b16 v41, v2 offset:52480
	v_mul_f32_e32 v2, v24, v48
	v_cvt_pk_bf16_f32 v2, v2, s0
	ds_write_b16 v41, v2 offset:52544
	v_mul_f32_e32 v2, v9, v49
	v_cvt_pk_bf16_f32 v2, v2, s0
	ds_write_b16 v41, v2 offset:52608
	v_mul_f32_e32 v2, v25, v49
	v_cvt_pk_bf16_f32 v2, v2, s0
	ds_write_b16 v41, v2 offset:52672
	v_mul_f32_e32 v2, v10, v0
	v_mul_f32_e32 v0, v26, v0
	v_cvt_pk_bf16_f32 v0, v0, s0
	ds_write_b16 v41, v0 offset:53312
	v_mul_f32_e32 v0, v11, v34
	v_cvt_pk_bf16_f32 v0, v0, s0
	ds_write_b16 v41, v0 offset:53376
	v_mul_f32_e32 v0, v27, v34
	v_cvt_pk_bf16_f32 v0, v0, s0
	ds_write_b16 v41, v0 offset:53440
	v_mul_f32_e32 v0, v12, v35
	v_cvt_pk_bf16_f32 v0, v0, s0
	ds_write_b16 v41, v0 offset:53504
	v_mul_f32_e32 v0, v28, v35
	v_cvt_pk_bf16_f32 v0, v0, s0
	ds_write_b16 v41, v0 offset:53568
	v_mul_f32_e32 v0, v13, v36
	v_cvt_pk_bf16_f32 v0, v0, s0
	ds_write_b16 v41, v0 offset:53632
	v_mul_f32_e32 v0, v29, v36
	v_cvt_pk_bf16_f32 v0, v0, s0
	ds_write_b16 v41, v0 offset:53696
	v_mul_f32_e32 v0, v14, v37
	v_cvt_pk_bf16_f32 v0, v0, s0
	ds_write_b16 v41, v0 offset:54272
	v_mul_f32_e32 v0, v30, v37
	v_cvt_pk_bf16_f32 v0, v0, s0
	ds_write_b16 v41, v0 offset:54336
	v_mul_f32_e32 v0, v15, v38
	v_cvt_pk_bf16_f32 v0, v0, s0
	ds_write_b16 v41, v0 offset:54400
	v_mul_f32_e32 v0, v31, v38
	v_cvt_pk_bf16_f32 v0, v0, s0
	ds_write_b16 v41, v0 offset:54464
	v_mul_f32_e32 v0, v16, v39
	v_cvt_pk_bf16_f32 v0, v0, s0
	ds_write_b16 v41, v0 offset:54528
	v_mul_f32_e32 v0, v32, v39
	v_cvt_pk_bf16_f32 v0, v0, s0
	ds_write_b16 v41, v0 offset:54592
	v_mul_f32_e32 v0, v17, v40
	v_cvt_pk_bf16_f32 v0, v0, s0
	ds_write_b16 v41, v0 offset:54656
	v_mul_f32_e32 v0, v33, v40
	v_cvt_pk_bf16_f32 v0, v0, s0
	ds_write_b16 v41, v0 offset:54720
	s_lshl_b64 s[4:5], s[24:25], 1
	v_lshlrev_b32_e32 v0, 1, v239
	v_cvt_pk_bf16_f32 v2, v2, s0
	s_add_u32 s4, s6, s4
	v_and_b32_e32 v0, 0x70, v0
	ds_write_b16 v41, v2 offset:53248
	s_addc_u32 s5, s7, s5
	v_lshrrev_b32_e32 v14, 3, v238
	v_add_u32_e32 v15, s26, v0
	s_waitcnt lgkmcnt(0)
	v_lshl_add_u64 v[2:3], s[4:5], 0, v[0:1]
	s_mov_b64 s[4:5], 0x13800400
	v_lshl_add_u32 v0, v14, 7, v15
	v_or_b32_e32 v16, 8, v14
	v_lshl_add_u64 v[10:11], v[2:3], 0, s[4:5]
	ds_read_b128 v[2:5], v0 offset:51200
	v_lshl_add_u32 v6, v16, 7, v15
	ds_read_b128 v[6:9], v6 offset:51200
	v_lshlrev_b32_e32 v0, 11, v14
	v_lshl_add_u64 v[12:13], v[10:11], 0, v[0:1]
	v_lshlrev_b32_e32 v0, 11, v16
	s_waitcnt lgkmcnt(1)
	global_store_dwordx4 v[12:13], v[2:5], off
	s_mov_b32 s4, 0
	s_nop 0
	v_lshl_add_u64 v[2:3], v[10:11], 0, v[0:1]
	v_or_b32_e32 v0, 16, v14
	s_waitcnt lgkmcnt(0)
	global_store_dwordx4 v[2:3], v[6:9], off
	v_lshl_add_u32 v2, v0, 7, v15
	v_or_b32_e32 v14, 24, v14
	ds_read_b128 v[2:5], v2 offset:51200
	v_lshl_add_u32 v6, v14, 7, v15
	ds_read_b128 v[6:9], v6 offset:51200
	v_lshlrev_b32_e32 v0, 11, v0
	v_lshl_add_u64 v[12:13], v[10:11], 0, v[0:1]
	v_lshlrev_b32_e32 v0, 11, v14
	s_waitcnt lgkmcnt(1)
	global_store_dwordx4 v[12:13], v[2:5], off
	s_nop 1
	v_lshl_add_u64 v[2:3], v[10:11], 0, v[0:1]
	s_waitcnt lgkmcnt(0)
	global_store_dwordx4 v[2:3], v[6:9], off
	s_waitcnt lgkmcnt(0)
	s_barrier
	s_setprio 0
	s_mov_b64 s[24:25], -1
	s_cmp_gt_i32 s4, 26
	s_mov_b64 s[26:27], -1
	s_cbranch_scc0 .LBB0_605
